# layer-0 weight conversion: the next tile of the mlp matrices is touched (4 MB ahead) while the current tile is converted
# speedup vs baseline: 1.0036x; 1.0036x over previous
; __device__ __forceinline__ void cvt_matrix(const float* __restrict__ src, int ldsrc, int K, int Nsrc, int Npad,
;                                            u16* __restrict__ dst, int& ctr, float* tl, int tid, int bid, int G) {
;     ...
;   for (int t = first; t < T; t += G) {
;     const int k0 = (t / nn) * 64, n0 = (t % nn) * 64;
;     {
;       const int r = tid >> 4, c4 = (tid & 15) * 4;
; #pragma unroll
;       for (int i = 0; i < 2; ++i) {
;         const int rr = r + 32 * i;
;         float4 v = make_float4(0.f, 0.f, 0.f, 0.f);
;         if (n0 + c4 < Nsrc) v = *(const float4*)(src + (size_t)(k0 + rr) * ldsrc + n0 + c4);
;         float* d = tl + rr * 65 + c4;
;         d[0] = v.x; d[1] = v.y; d[2] = v.z; d[3] = v.w;
;       }
;     }
;     __syncthreads();
;     {
;       const int n = tid >> 3, k8 = (tid & 7) * 8;
;       float f[8];
; #pragma unroll
;       for (int i = 0; i < 8; ++i) f[i] = tl[(k8 + i) * 65 + n];
;       u32x4 w = {cvtpk(f[0], f[1]), cvtpk(f[2], f[3]), cvtpk(f[4], f[5]), cvtpk(f[6], f[7])};
;       *(u32x4*)(dst + (size_t)(n0 + n) * K + k0 + k8) = w;
;     }
;     __syncthreads();
;   }
.LBB0_784:
	s_or_b64 exec, exec, s[6:7]
	s_waitcnt vmcnt(3)
	ds_write2_b32 v16, v0, v1 offset1:1
	ds_write2_b32 v16, v2, v3 offset0:2 offset1:3
	v_add_u32_e32 v0, 0x2080, v16
	s_waitcnt vmcnt(2)
	ds_write2_b32 v0, v4, v5 offset1:1
	v_add_u32_e32 v0, 0x2088, v16
	ds_write2_b32 v0, v6, v7 offset1:1
	s_waitcnt lgkmcnt(0)
	s_barrier
	ds_read2_b32 v[0:1], v17 offset1:65
	ds_read2_b32 v[2:3], v17 offset0:130 offset1:195
	v_add_u32_e32 v6, 0x400, v17
	ds_read2_b32 v[4:5], v6 offset0:4 offset1:69
	ds_read2_b32 v[6:7], v6 offset0:134 offset1:199
	s_add_i32 s5, s5, s9
	s_waitcnt lgkmcnt(3)
	v_cvt_pk_bf16_f32 v0, v0, v1
	s_waitcnt lgkmcnt(2)
	v_cvt_pk_bf16_f32 v1, v2, v3
	s_waitcnt lgkmcnt(1)
	v_cvt_pk_bf16_f32 v2, v4, v5
	v_add_u32_e32 v4, s5, v12
	v_ashrrev_i32_e32 v5, 31, v4
	v_readlane_b32 s6, v253, 9
	v_lshlrev_b64 v[4:5], 11, v[4:5]
	v_readlane_b32 s7, v253, 10
	s_ashr_i32 s5, s4, 31
	s_add_i32 s8, s8, s71
	v_lshl_add_u64 v[4:5], s[6:7], 0, v[4:5]
	v_lshl_add_u64 v[4:5], s[4:5], 1, v[4:5]
	s_add_i32 s9, s9, s10
	v_lshl_add_u64 v[4:5], v[4:5], 0, v[200:201]
	s_cmpk_lt_i32 s8, 0x400
	s_waitcnt lgkmcnt(0)
	v_cvt_pk_bf16_f32 v3, v6, v7
	global_store_dwordx4 v[4:5], v[0:3], off
	s_barrier
	s_cbranch_scc0 .LBB0_787
.LBB0_785:
	s_ashr_i32 s4, s8, 31
	s_lshr_b32 s4, s4, 26
	s_add_i32 s5, s8, s4
	s_and_b32 s4, s5, 0xffffffc0
	s_lshl_b32 s5, s5, 6
	s_and_b32 s6, s5, 0xfffff000
	s_sub_i32 s5, 0, s6
	s_sub_i32 s6, s9, s6
	v_add_u32_e32 v0, s6, v15
	s_movk_i32 s6, 0x1000
	v_cmp_gt_i32_e32 vcc, s6, v0
	v_mov_b32_e32 v0, 0
	v_mov_b32_e32 v1, 0
	v_mov_b32_e32 v2, 0
	v_mov_b32_e32 v3, 0
	v_mov_b32_e32 v4, 0
	v_mov_b32_e32 v5, 0
	v_mov_b32_e32 v6, 0
	v_mov_b32_e32 v7, 0
	s_and_saveexec_b64 s[6:7], vcc
	s_cbranch_execz .LBB0_784
	v_add_u32_e32 v2, s4, v9
	v_ashrrev_i32_e32 v3, 31, v2
	s_add_i32 s18, s9, s5
	v_lshlrev_b64 v[4:5], 14, v[2:3]
	v_add_u32_e32 v2, 32, v2
	s_ashr_i32 s19, s18, 31
	v_ashrrev_i32_e32 v3, 31, v2
	v_lshl_add_u64 v[0:1], s[18:19], 2, v[10:11]
	v_lshlrev_b64 v[2:3], 14, v[2:3]
	v_lshl_add_u64 v[4:5], v[0:1], 0, v[4:5]
	v_lshl_add_u64 v[6:7], v[0:1], 0, v[2:3]
	v_add_co_u32_e32 v18, vcc, 0x400000, v4
	s_nop 1
	v_addc_co_u32_e32 v19, vcc, 0, v5, vcc
	v_add_co_u32_e32 v20, vcc, 0x400000, v6
	s_nop 1
	v_addc_co_u32_e32 v21, vcc, 0, v7, vcc
	global_load_dwordx4 v[0:3], v[4:5], off
	s_nop 0
	global_load_dwordx4 v[4:7], v[6:7], off
	global_load_dword v248, v[18:19], off
	global_load_dword v249, v[20:21], off
	s_branch .LBB0_784

; __device__ __forceinline__ void cvt_matrix(const float* __restrict__ src, int ldsrc, int K, int Nsrc, int Npad,
;                                            u16* __restrict__ dst, int& ctr, float* tl, int tid, int bid, int G) {
;     ...
;   for (int t = first; t < T; t += G) {
;     const int k0 = (t / nn) * 64, n0 = (t % nn) * 64;
;     {
;       const int r = tid >> 4, c4 = (tid & 15) * 4;
; #pragma unroll
;       for (int i = 0; i < 2; ++i) {
;         const int rr = r + 32 * i;
;         float4 v = make_float4(0.f, 0.f, 0.f, 0.f);
;         if (n0 + c4 < Nsrc) v = *(const float4*)(src + (size_t)(k0 + rr) * ldsrc + n0 + c4);
;         float* d = tl + rr * 65 + c4;
;         d[0] = v.x; d[1] = v.y; d[2] = v.z; d[3] = v.w;
;       }
;     }
;     __syncthreads();
;     {
;       const int n = tid >> 3, k8 = (tid & 7) * 8;
;       float f[8];
; #pragma unroll
;       for (int i = 0; i < 8; ++i) f[i] = tl[(k8 + i) * 65 + n];
;       u32x4 w = {cvtpk(f[0], f[1]), cvtpk(f[2], f[3]), cvtpk(f[4], f[5]), cvtpk(f[6], f[7])};
;       *(u32x4*)(dst + (size_t)(n0 + n) * K + k0 + k8) = w;
;     }
;     __syncthreads();
;   }
.LBB0_789:
	s_or_b64 exec, exec, s[4:5]
	s_waitcnt vmcnt(3)
	ds_write2_b32 v14, v0, v1 offset1:1
	ds_write2_b32 v14, v2, v3 offset0:2 offset1:3
	v_add_u32_e32 v0, 0x2080, v14
	s_waitcnt vmcnt(2)
	ds_write2_b32 v0, v4, v5 offset1:1
	v_add_u32_e32 v0, 0x2088, v14
	ds_write2_b32 v0, v6, v7 offset1:1
	s_waitcnt lgkmcnt(0)
	s_barrier
	ds_read2_b32 v[0:1], v13 offset1:65
	ds_read2_b32 v[2:3], v13 offset0:130 offset1:195
	v_add_u32_e32 v6, 0x400, v13
	ds_read2_b32 v[4:5], v6 offset0:4 offset1:69
	ds_read2_b32 v[6:7], v6 offset0:134 offset1:199
	s_add_i32 s1, s1, s7
	s_waitcnt lgkmcnt(3)
	v_cvt_pk_bf16_f32 v0, v0, v1
	s_waitcnt lgkmcnt(2)
	v_cvt_pk_bf16_f32 v1, v2, v3
	s_waitcnt lgkmcnt(1)
	v_cvt_pk_bf16_f32 v2, v4, v5
	v_add_u32_e32 v4, s1, v12
	v_ashrrev_i32_e32 v5, 31, v4
	v_readlane_b32 s4, v253, 21
	v_lshlrev_b64 v[4:5], 13, v[4:5]
	v_readlane_b32 s5, v253, 22
	s_ashr_i32 s1, s0, 31
	s_add_i32 s6, s6, s71
	v_lshl_add_u64 v[4:5], s[4:5], 0, v[4:5]
	v_lshl_add_u64 v[4:5], s[0:1], 1, v[4:5]
	s_add_i32 s7, s7, s8
	v_lshl_add_u64 v[4:5], v[4:5], 0, v[200:201]
	s_cmpk_lt_i32 s6, 0x400
	s_waitcnt lgkmcnt(0)
	v_cvt_pk_bf16_f32 v3, v6, v7
	global_store_dwordx4 v[4:5], v[0:3], off
	s_barrier
	s_cbranch_scc0 .LBB0_792
.LBB0_790:
	s_ashr_i32 s0, s6, 31
	s_lshr_b32 s0, s0, 28
	s_add_i32 s0, s6, s0
	s_ashr_i32 s1, s0, 4
	s_lshl_b32 s4, s1, 10
	s_lshl_b32 s0, s1, 6
	s_sub_i32 s1, 0, s4
	s_sub_i32 s4, s7, s4
	v_add_u32_e32 v0, s4, v15
	s_movk_i32 s4, 0x400
	v_cmp_gt_i32_e32 vcc, s4, v0
	v_mov_b32_e32 v0, 0
	v_mov_b32_e32 v1, 0
	v_mov_b32_e32 v2, 0
	v_mov_b32_e32 v3, 0
	v_mov_b32_e32 v4, 0
	v_mov_b32_e32 v5, 0
	v_mov_b32_e32 v6, 0
	v_mov_b32_e32 v7, 0
	s_and_saveexec_b64 s[4:5], vcc
	s_cbranch_execz .LBB0_789
	v_add_u32_e32 v2, s0, v9
	v_ashrrev_i32_e32 v3, 31, v2
	s_add_i32 s10, s7, s1
	v_lshlrev_b64 v[4:5], 12, v[2:3]
	v_add_u32_e32 v2, 32, v2
	s_ashr_i32 s11, s10, 31
	v_ashrrev_i32_e32 v3, 31, v2
	v_lshl_add_u64 v[0:1], s[10:11], 2, v[10:11]
	v_lshlrev_b64 v[2:3], 12, v[2:3]
	v_lshl_add_u64 v[4:5], v[0:1], 0, v[4:5]
	v_lshl_add_u64 v[6:7], v[0:1], 0, v[2:3]
	v_add_co_u32_e32 v18, vcc, 0x400000, v4
	s_nop 1
	v_addc_co_u32_e32 v19, vcc, 0, v5, vcc
	v_add_co_u32_e32 v20, vcc, 0x400000, v6
	s_nop 1
	v_addc_co_u32_e32 v21, vcc, 0, v7, vcc
	global_load_dwordx4 v[0:3], v[4:5], off
	s_nop 0
	global_load_dwordx4 v[4:7], v[6:7], off
	global_load_dword v248, v[18:19], off
	global_load_dword v249, v[20:21], off
	s_branch .LBB0_789
